# v43 + ssm_a second-half U tile staged by direct global->LDS loads into the unused lower 64 KB of LDS, issued during the first half (strategy: direct HBM->LDS loads)
# baseline (speedup 1.0000x reference)
; #define LAS __attribute__((address_space(3)))
; __device__ __forceinline__ void ssm_stage_u(unsigned char* ws, LAS unsigned char* lds, int g, int cb, int hh, int tid) {
;     asm volatile("" : "+v"(tid));
;     const bf16* U = (const bf16*)(ws + AR_U);
;     u32x4 v[8];
; #pragma unroll
;     for (int r = 0; r < 8; ++r) { const int c = r * 512 + tid, jj = c >> 7, col = (c >> 1) & 63, part = c & 1;
;         v[r] = *(const u32x4*)(U + ((size_t)((cb * 64 + col) * 64 + hh * 32 + jj) * 512 + g * 16 + part * 8)); }
; #pragma unroll
;     for (int r = 0; r < 8; ++r) { const int c = r * 512 + tid; *(LAS u32x4*)(lds + SS_UB + c * 16) = v[r]; }
; }
; __device__ __forceinline__ void ssm_a_task(unsigned char* ws, LAS unsigned char* lds, int task, int tid) {
;     ...
;     f32x4 acc[2][4];
; #pragma unroll
;     for (int a = 0; a < 2; ++a)
; #pragma unroll
;         for (int c = 0; c < 4; ++c) acc[a][c] = (f32x4){0.f, 0.f, 0.f, 0.f};
;     const bf16* WA = (const bf16*)(ws + WS_WA) + ((size_t)(g * 256 + wid * 32 + rr) * 1024 + 8 * kk);
;     for (int hh = 0; hh < 2; ++hh) {
;         ssm_stage_u(ws, lds, g, cb, hh, tid);
;         __syncthreads();
; #pragma unroll 4
;         for (int ks = 0; ks < 16; ++ks) {
;             bf16x8 bfr[4], afr[2];
; #pragma unroll
;             for (int a = 0; a < 2; ++a) afr[a] = *(const bf16x8*)(WA + (size_t)a * 16 * 1024 + (hh * 16 + ks) * 32);
.LBB0_603:
	s_ashr_i32 s16, s54, 3
	v_mov_b32_e32 v30, v44
	s_and_b32 s17, s54, 7
	s_lshl_b32 s14, s16, 4
	s_lshl_b32 s3, s17, 12
	v_lshlrev_b32_e32 v0, 5, v30
	s_ashr_i32 s15, s14, 31
	v_and_b32_e32 v0, 0xfc0, v0
	s_lshl_b64 s[14:15], s[14:15], 1
	v_or_b32_e32 v31, s3, v0
	v_ashrrev_i32_e32 v0, 7, v30
	v_add_u32_e32 v4, 0x200, v30
	s_add_u32 s34, s4, s14
	s_waitcnt vmcnt(1)
	v_lshlrev_b32_e32 v38, 4, v30
	v_add_u32_e32 v0, v31, v0
	v_ashrrev_i32_e32 v4, 7, v4
	v_add_u32_e32 v8, 0x400, v30
	s_addc_u32 s35, s5, s15
	v_and_b32_e32 v184, 16, v38
	v_ashrrev_i32_e32 v1, 31, v0
	v_add_u32_e32 v4, v31, v4
	v_ashrrev_i32_e32 v8, 7, v8
	v_add_u32_e32 v12, 0x600, v30
	v_lshl_add_u64 v[28:29], s[34:35], 0, v[184:185]
	v_lshlrev_b64 v[0:1], 10, v[0:1]
	v_ashrrev_i32_e32 v5, 31, v4
	v_add_u32_e32 v8, v31, v8
	v_ashrrev_i32_e32 v12, 7, v12
	v_add_u32_e32 v16, 0x800, v30
	v_lshl_add_u64 v[0:1], v[28:29], 0, v[0:1]
	v_lshlrev_b64 v[4:5], 10, v[4:5]
	v_ashrrev_i32_e32 v9, 31, v8
	v_add_u32_e32 v12, v31, v12
	v_ashrrev_i32_e32 v16, 7, v16
	v_add_u32_e32 v20, 0xa00, v30
	s_mov_b32 s100, 0x8000
	s_mov_b32 s101, 0
	v_lshl_add_u64 v[134:135], v[0:1], 0, s[100:101]
	global_load_dwordx4 v[0:3], v[0:1], off
	v_lshl_add_u64 v[4:5], v[28:29], 0, v[4:5]
	v_lshlrev_b64 v[8:9], 10, v[8:9]
	v_ashrrev_i32_e32 v13, 31, v12
	v_add_u32_e32 v16, v31, v16
	v_ashrrev_i32_e32 v20, 7, v20
	v_add_u32_e32 v24, 0xc00, v30
	v_lshl_add_u64 v[136:137], v[4:5], 0, s[100:101]
	global_load_dwordx4 v[4:7], v[4:5], off
	v_lshl_add_u64 v[8:9], v[28:29], 0, v[8:9]
	v_lshlrev_b64 v[12:13], 10, v[12:13]
	v_ashrrev_i32_e32 v17, 31, v16
	v_add_u32_e32 v20, v31, v20
	v_ashrrev_i32_e32 v24, 7, v24
	v_add_u32_e32 v30, 0xe00, v30
	v_lshl_add_u64 v[138:139], v[8:9], 0, s[100:101]
	global_load_dwordx4 v[8:11], v[8:9], off
	v_lshl_add_u64 v[12:13], v[28:29], 0, v[12:13]
	v_lshlrev_b64 v[16:17], 10, v[16:17]
	v_ashrrev_i32_e32 v21, 31, v20
	v_add_u32_e32 v24, v31, v24
	v_ashrrev_i32_e32 v30, 7, v30
	v_lshl_add_u64 v[140:141], v[12:13], 0, s[100:101]
	global_load_dwordx4 v[12:15], v[12:13], off
	v_lshl_add_u64 v[16:17], v[28:29], 0, v[16:17]
	v_lshlrev_b64 v[20:21], 10, v[20:21]
	v_ashrrev_i32_e32 v25, 31, v24
	v_add_u32_e32 v30, v31, v30
	v_lshl_add_u64 v[142:143], v[16:17], 0, s[100:101]
	global_load_dwordx4 v[16:19], v[16:17], off
	v_lshl_add_u64 v[20:21], v[28:29], 0, v[20:21]
	v_lshlrev_b64 v[24:25], 10, v[24:25]
	v_ashrrev_i32_e32 v31, 31, v30
	v_lshl_add_u64 v[144:145], v[20:21], 0, s[100:101]
	global_load_dwordx4 v[20:23], v[20:21], off
	v_lshl_add_u64 v[24:25], v[28:29], 0, v[24:25]
	v_lshlrev_b64 v[30:31], 10, v[30:31]
	v_lshl_add_u64 v[146:147], v[24:25], 0, s[100:101]
	global_load_dwordx4 v[24:27], v[24:25], off
	v_lshl_add_u64 v[28:29], v[28:29], 0, v[30:31]
	v_lshl_add_u64 v[148:149], v[28:29], 0, s[100:101]
	global_load_dwordx4 v[28:31], v[28:29], off
	v_add_u32_e32 v38, 0, v38
	v_add_u32_e32 v38, 0x10000, v38
	s_mov_b32 s12, 0
	v_lshl_add_u32 v132, s16, 8, v46
	v_ashrrev_i32_e32 v133, 31, v132
	v_lshlrev_b64 v[132:133], 11, v[132:133]
	v_lshl_add_u64 v[40:41], v[34:35], 0, v[132:133]
	v_add_co_u32_e32 v164, vcc, 0xffff8000, v40
	s_nop 1
	v_addc_co_u32_e32 v165, vcc, -1, v41, vcc
	global_load_dwordx4 v[80:83], v[40:41], off offset:-192
	global_load_dwordx4 v[84:87], v[164:165], off offset:-192
	global_load_dwordx4 v[88:91], v[40:41], off offset:-128
	global_load_dwordx4 v[92:95], v[164:165], off offset:-128
	global_load_dwordx4 v[96:99], v[40:41], off offset:-64
	global_load_dwordx4 v[100:103], v[164:165], off offset:-64
	global_load_dwordx4 v[104:107], v[40:41], off offset:0
	global_load_dwordx4 v[108:111], v[164:165], off offset:0
	global_load_dwordx4 v[112:115], v[40:41], off offset:64
	global_load_dwordx4 v[116:119], v[164:165], off offset:64
	global_load_dwordx4 v[120:123], v[40:41], off offset:128
	global_load_dwordx4 v[124:127], v[164:165], off offset:128
	global_load_dwordx4 v[128:131], v[40:41], off offset:192
	global_load_dwordx4 v[168:171], v[164:165], off offset:192
	global_load_dwordx4 v[172:175], v[40:41], off offset:256
	global_load_dwordx4 v[176:179], v[164:165], off offset:256
	global_load_dwordx4 v[180:183], v[40:41], off offset:320
	global_load_dwordx4 v[186:189], v[164:165], off offset:320
	global_load_dwordx4 v[190:193], v[40:41], off offset:384
	global_load_dwordx4 v[194:197], v[164:165], off offset:384
	global_load_dwordx4 v[198:201], v[40:41], off offset:448
	global_load_dwordx4 v[202:205], v[164:165], off offset:448
	global_load_dwordx4 v[206:209], v[40:41], off offset:512
	global_load_dwordx4 v[210:213], v[164:165], off offset:512
	s_lshl_b32 m0, s77, 10
	s_nop 0
	global_load_lds_dwordx4 v[134:135], off
	s_add_i32 m0, m0, 0x2000
	s_nop 0
	global_load_lds_dwordx4 v[136:137], off
	s_add_i32 m0, m0, 0x2000
	s_nop 0
	global_load_lds_dwordx4 v[138:139], off
	s_add_i32 m0, m0, 0x2000
	s_nop 0
	global_load_lds_dwordx4 v[140:141], off
	s_add_i32 m0, m0, 0x2000
	s_nop 0
	global_load_lds_dwordx4 v[142:143], off
	s_add_i32 m0, m0, 0x2000
	s_nop 0
	global_load_lds_dwordx4 v[144:145], off
	s_add_i32 m0, m0, 0x2000
	s_nop 0
	global_load_lds_dwordx4 v[146:147], off
	s_add_i32 m0, m0, 0x2000
	s_nop 0
	global_load_lds_dwordx4 v[148:149], off
	s_waitcnt vmcnt(39)
	ds_write_b128 v38, v[0:3]
	s_waitcnt vmcnt(38)
	ds_write_b128 v38, v[4:7] offset:8192
	s_waitcnt vmcnt(37)
	ds_write_b128 v38, v[8:11] offset:16384
	s_waitcnt vmcnt(36)
	ds_write_b128 v38, v[12:15] offset:24576
	s_waitcnt vmcnt(35)
	ds_write_b128 v38, v[16:19] offset:32768
	s_waitcnt vmcnt(34)
	ds_write_b128 v38, v[20:23] offset:40960
	s_waitcnt vmcnt(33)
	ds_write_b128 v38, v[24:27] offset:49152
	s_waitcnt vmcnt(32)
	ds_write_b128 v38, v[28:31] offset:57344
	v_lshl_add_u32 v0, s16, 8, v46
	v_ashrrev_i32_e32 v1, 31, v0
	v_lshlrev_b64 v[38:39], 11, v[0:1]
	v_mov_b32_e32 v0, 0
	v_lshl_add_u64 v[40:41], v[34:35], 0, v[38:39]
	v_mov_b32_e32 v1, v0
	v_mov_b32_e32 v2, v0
	v_mov_b32_e32 v3, v0
	v_mov_b32_e32 v4, v0
	v_mov_b32_e32 v5, v0
	v_mov_b32_e32 v6, v0
	v_mov_b32_e32 v7, v0
	v_mov_b32_e32 v8, v0
	v_mov_b32_e32 v9, v0
	v_mov_b32_e32 v10, v0
	v_mov_b32_e32 v11, v0
	v_mov_b32_e32 v12, v0
	v_mov_b32_e32 v13, v0
	v_mov_b32_e32 v14, v0
	v_mov_b32_e32 v15, v0
	v_mov_b32_e32 v16, v0
	v_mov_b32_e32 v17, v0
	v_mov_b32_e32 v18, v0
	v_mov_b32_e32 v19, v0
	v_mov_b32_e32 v20, v0
	v_mov_b32_e32 v21, v0
	v_mov_b32_e32 v22, v0
	v_mov_b32_e32 v23, v0
	v_mov_b32_e32 v24, v0
	v_mov_b32_e32 v25, v0
	v_mov_b32_e32 v26, v0
	v_mov_b32_e32 v27, v0
	v_mov_b32_e32 v28, v0
	v_mov_b32_e32 v29, v0
	v_mov_b32_e32 v30, v0
	v_mov_b32_e32 v31, v0
	s_waitcnt lgkmcnt(0)
	s_barrier
; #define LAS __attribute__((address_space(3)))
; __device__ __forceinline__ void ssm_a_task(unsigned char* ws, LAS unsigned char* lds, int task, int tid) {
;     ...
; #pragma unroll 4
;         for (int ks = 0; ks < 16; ++ks) {
;             bf16x8 bfr[4], afr[2];
; #pragma unroll
;             for (int a = 0; a < 2; ++a) afr[a] = *(const bf16x8*)(WA + (size_t)a * 16 * 1024 + (hh * 16 + ks) * 32);
; #pragma unroll
;             for (int c = 0; c < 4; ++c) bfr[c] = *(const LAS bf16x8*)(lds + SS_UB + (((2 * ks + (kk >> 1)) * 64 + c * 16 + rr) * 32 + (kk & 1) * 16));
; #pragma unroll
;             for (int a = 0; a < 2; ++a)
; #pragma unroll
;                 for (int c = 0; c < 4; ++c) acc[a][c] = __builtin_amdgcn_mfma_f32_16x16x32_bf16(afr[a], bfr[c], acc[a][c], 0, 0, 0);
;         }
.LBB0_604:
	v_add_u32_e32 v166, 0x10000, v47
	ds_read_b128 v[132:135], v166 offset:0
	ds_read_b128 v[136:139], v166 offset:512
	ds_read_b128 v[140:143], v166 offset:1024
	ds_read_b128 v[144:147], v166 offset:1536
	ds_read_b128 v[148:151], v166 offset:4096
	ds_read_b128 v[152:155], v166 offset:4608
	ds_read_b128 v[156:159], v166 offset:5120
	ds_read_b128 v[160:163], v166 offset:5632
	s_waitcnt lgkmcnt(4)
	s_waitcnt vmcnt(31)
	v_mfma_f32_16x16x32_bf16 v[12:15], v[80:83], v[132:135], v[12:15]
	v_mfma_f32_16x16x32_bf16 v[8:11], v[80:83], v[136:139], v[8:11]
	v_mfma_f32_16x16x32_bf16 v[4:7], v[80:83], v[140:143], v[4:7]
	v_mfma_f32_16x16x32_bf16 v[0:3], v[80:83], v[144:147], v[0:3]
	s_waitcnt vmcnt(30)
	v_mfma_f32_16x16x32_bf16 v[28:31], v[84:87], v[132:135], v[28:31]
	v_mfma_f32_16x16x32_bf16 v[24:27], v[84:87], v[136:139], v[24:27]
	v_mfma_f32_16x16x32_bf16 v[20:23], v[84:87], v[140:143], v[20:23]
	v_mfma_f32_16x16x32_bf16 v[16:19], v[84:87], v[144:147], v[16:19]
	global_load_dwordx4 v[80:83], v[40:41], off offset:576
	global_load_dwordx4 v[84:87], v[164:165], off offset:576
	ds_read_b128 v[132:135], v166 offset:8192
	ds_read_b128 v[136:139], v166 offset:8704
	ds_read_b128 v[140:143], v166 offset:9216
	ds_read_b128 v[144:147], v166 offset:9728
	s_waitcnt lgkmcnt(4)
	s_waitcnt vmcnt(31)
	v_mfma_f32_16x16x32_bf16 v[12:15], v[88:91], v[148:151], v[12:15]
	v_mfma_f32_16x16x32_bf16 v[8:11], v[88:91], v[152:155], v[8:11]
	v_mfma_f32_16x16x32_bf16 v[4:7], v[88:91], v[156:159], v[4:7]
	v_mfma_f32_16x16x32_bf16 v[0:3], v[88:91], v[160:163], v[0:3]
	s_waitcnt vmcnt(30)
	v_mfma_f32_16x16x32_bf16 v[28:31], v[92:95], v[148:151], v[28:31]
	v_mfma_f32_16x16x32_bf16 v[24:27], v[92:95], v[152:155], v[24:27]
	v_mfma_f32_16x16x32_bf16 v[20:23], v[92:95], v[156:159], v[20:23]
	v_mfma_f32_16x16x32_bf16 v[16:19], v[92:95], v[160:163], v[16:19]
	global_load_dwordx4 v[88:91], v[40:41], off offset:640
	global_load_dwordx4 v[92:95], v[164:165], off offset:640
	ds_read_b128 v[148:151], v166 offset:12288
	ds_read_b128 v[152:155], v166 offset:12800
	ds_read_b128 v[156:159], v166 offset:13312
	ds_read_b128 v[160:163], v166 offset:13824
	s_waitcnt lgkmcnt(4)
	s_waitcnt vmcnt(31)
	v_mfma_f32_16x16x32_bf16 v[12:15], v[96:99], v[132:135], v[12:15]
	v_mfma_f32_16x16x32_bf16 v[8:11], v[96:99], v[136:139], v[8:11]
	v_mfma_f32_16x16x32_bf16 v[4:7], v[96:99], v[140:143], v[4:7]
	v_mfma_f32_16x16x32_bf16 v[0:3], v[96:99], v[144:147], v[0:3]
	s_waitcnt vmcnt(30)
	v_mfma_f32_16x16x32_bf16 v[28:31], v[100:103], v[132:135], v[28:31]
	v_mfma_f32_16x16x32_bf16 v[24:27], v[100:103], v[136:139], v[24:27]
	v_mfma_f32_16x16x32_bf16 v[20:23], v[100:103], v[140:143], v[20:23]
	v_mfma_f32_16x16x32_bf16 v[16:19], v[100:103], v[144:147], v[16:19]
	global_load_dwordx4 v[96:99], v[40:41], off offset:704
	global_load_dwordx4 v[100:103], v[164:165], off offset:704
	ds_read_b128 v[132:135], v166 offset:16384
	ds_read_b128 v[136:139], v166 offset:16896
	ds_read_b128 v[140:143], v166 offset:17408
	ds_read_b128 v[144:147], v166 offset:17920
	s_waitcnt lgkmcnt(4)
	s_waitcnt vmcnt(31)
	v_mfma_f32_16x16x32_bf16 v[12:15], v[104:107], v[148:151], v[12:15]
	v_mfma_f32_16x16x32_bf16 v[8:11], v[104:107], v[152:155], v[8:11]
	v_mfma_f32_16x16x32_bf16 v[4:7], v[104:107], v[156:159], v[4:7]
	v_mfma_f32_16x16x32_bf16 v[0:3], v[104:107], v[160:163], v[0:3]
	s_waitcnt vmcnt(30)
	v_mfma_f32_16x16x32_bf16 v[28:31], v[108:111], v[148:151], v[28:31]
	v_mfma_f32_16x16x32_bf16 v[24:27], v[108:111], v[152:155], v[24:27]
	v_mfma_f32_16x16x32_bf16 v[20:23], v[108:111], v[156:159], v[20:23]
	v_mfma_f32_16x16x32_bf16 v[16:19], v[108:111], v[160:163], v[16:19]
	global_load_dwordx4 v[104:107], v[40:41], off offset:768
	global_load_dwordx4 v[108:111], v[164:165], off offset:768
	ds_read_b128 v[148:151], v166 offset:20480
	ds_read_b128 v[152:155], v166 offset:20992
	ds_read_b128 v[156:159], v166 offset:21504
	ds_read_b128 v[160:163], v166 offset:22016
	s_waitcnt lgkmcnt(4)
	s_waitcnt vmcnt(31)
	v_mfma_f32_16x16x32_bf16 v[12:15], v[112:115], v[132:135], v[12:15]
	v_mfma_f32_16x16x32_bf16 v[8:11], v[112:115], v[136:139], v[8:11]
	v_mfma_f32_16x16x32_bf16 v[4:7], v[112:115], v[140:143], v[4:7]
	v_mfma_f32_16x16x32_bf16 v[0:3], v[112:115], v[144:147], v[0:3]
	s_waitcnt vmcnt(30)
	v_mfma_f32_16x16x32_bf16 v[28:31], v[116:119], v[132:135], v[28:31]
	v_mfma_f32_16x16x32_bf16 v[24:27], v[116:119], v[136:139], v[24:27]
	v_mfma_f32_16x16x32_bf16 v[20:23], v[116:119], v[140:143], v[20:23]
	v_mfma_f32_16x16x32_bf16 v[16:19], v[116:119], v[144:147], v[16:19]
	ds_read_b128 v[132:135], v166 offset:24576
	ds_read_b128 v[136:139], v166 offset:25088
	ds_read_b128 v[140:143], v166 offset:25600
	ds_read_b128 v[144:147], v166 offset:26112
	s_waitcnt lgkmcnt(4)
	s_waitcnt vmcnt(29)
	v_mfma_f32_16x16x32_bf16 v[12:15], v[120:123], v[148:151], v[12:15]
	v_mfma_f32_16x16x32_bf16 v[8:11], v[120:123], v[152:155], v[8:11]
	v_mfma_f32_16x16x32_bf16 v[4:7], v[120:123], v[156:159], v[4:7]
	v_mfma_f32_16x16x32_bf16 v[0:3], v[120:123], v[160:163], v[0:3]
	s_waitcnt vmcnt(28)
	v_mfma_f32_16x16x32_bf16 v[28:31], v[124:127], v[148:151], v[28:31]
	v_mfma_f32_16x16x32_bf16 v[24:27], v[124:127], v[152:155], v[24:27]
	v_mfma_f32_16x16x32_bf16 v[20:23], v[124:127], v[156:159], v[20:23]
	v_mfma_f32_16x16x32_bf16 v[16:19], v[124:127], v[160:163], v[16:19]
	ds_read_b128 v[148:151], v166 offset:28672
	ds_read_b128 v[152:155], v166 offset:29184
	ds_read_b128 v[156:159], v166 offset:29696
	ds_read_b128 v[160:163], v166 offset:30208
	s_waitcnt lgkmcnt(4)
	s_waitcnt vmcnt(27)
; #define LAS __attribute__((address_space(3)))
; __device__ __forceinline__ void ssm_a_task(unsigned char* ws, LAS unsigned char* lds, int task, int tid) {
;     ...
; #pragma unroll 4
;         for (int ks = 0; ks < 16; ++ks) {
;             bf16x8 bfr[4], afr[2];
; #pragma unroll
;             for (int a = 0; a < 2; ++a) afr[a] = *(const bf16x8*)(WA + (size_t)a * 16 * 1024 + (hh * 16 + ks) * 32);
; #pragma unroll
;             for (int c = 0; c < 4; ++c) bfr[c] = *(const LAS bf16x8*)(lds + SS_UB + (((2 * ks + (kk >> 1)) * 64 + c * 16 + rr) * 32 + (kk & 1) * 16));
; #pragma unroll
;             for (int a = 0; a < 2; ++a)
; #pragma unroll
;                 for (int c = 0; c < 4; ++c) acc[a][c] = __builtin_amdgcn_mfma_f32_16x16x32_bf16(afr[a], bfr[c], acc[a][c], 0, 0, 0);
;         }
	v_mfma_f32_16x16x32_bf16 v[12:15], v[128:131], v[132:135], v[12:15]
	v_mfma_f32_16x16x32_bf16 v[8:11], v[128:131], v[136:139], v[8:11]
	v_mfma_f32_16x16x32_bf16 v[4:7], v[128:131], v[140:143], v[4:7]
	v_mfma_f32_16x16x32_bf16 v[0:3], v[128:131], v[144:147], v[0:3]
	s_waitcnt vmcnt(26)
	v_mfma_f32_16x16x32_bf16 v[28:31], v[168:171], v[132:135], v[28:31]
	v_mfma_f32_16x16x32_bf16 v[24:27], v[168:171], v[136:139], v[24:27]
	v_mfma_f32_16x16x32_bf16 v[20:23], v[168:171], v[140:143], v[20:23]
	v_mfma_f32_16x16x32_bf16 v[16:19], v[168:171], v[144:147], v[16:19]
	ds_read_b128 v[132:135], v166 offset:32768
	ds_read_b128 v[136:139], v166 offset:33280
	ds_read_b128 v[140:143], v166 offset:33792
	ds_read_b128 v[144:147], v166 offset:34304
	s_waitcnt lgkmcnt(4)
	s_waitcnt vmcnt(25)
	v_mfma_f32_16x16x32_bf16 v[12:15], v[172:175], v[148:151], v[12:15]
	v_mfma_f32_16x16x32_bf16 v[8:11], v[172:175], v[152:155], v[8:11]
	v_mfma_f32_16x16x32_bf16 v[4:7], v[172:175], v[156:159], v[4:7]
	v_mfma_f32_16x16x32_bf16 v[0:3], v[172:175], v[160:163], v[0:3]
	s_waitcnt vmcnt(24)
	v_mfma_f32_16x16x32_bf16 v[28:31], v[176:179], v[148:151], v[28:31]
	v_mfma_f32_16x16x32_bf16 v[24:27], v[176:179], v[152:155], v[24:27]
	v_mfma_f32_16x16x32_bf16 v[20:23], v[176:179], v[156:159], v[20:23]
	v_mfma_f32_16x16x32_bf16 v[16:19], v[176:179], v[160:163], v[16:19]
	ds_read_b128 v[148:151], v166 offset:36864
	ds_read_b128 v[152:155], v166 offset:37376
	ds_read_b128 v[156:159], v166 offset:37888
	ds_read_b128 v[160:163], v166 offset:38400
	s_waitcnt lgkmcnt(4)
	s_waitcnt vmcnt(23)
	v_mfma_f32_16x16x32_bf16 v[12:15], v[180:183], v[132:135], v[12:15]
	v_mfma_f32_16x16x32_bf16 v[8:11], v[180:183], v[136:139], v[8:11]
	v_mfma_f32_16x16x32_bf16 v[4:7], v[180:183], v[140:143], v[4:7]
	v_mfma_f32_16x16x32_bf16 v[0:3], v[180:183], v[144:147], v[0:3]
	s_waitcnt vmcnt(22)
	v_mfma_f32_16x16x32_bf16 v[28:31], v[186:189], v[132:135], v[28:31]
	v_mfma_f32_16x16x32_bf16 v[24:27], v[186:189], v[136:139], v[24:27]
	v_mfma_f32_16x16x32_bf16 v[20:23], v[186:189], v[140:143], v[20:23]
	v_mfma_f32_16x16x32_bf16 v[16:19], v[186:189], v[144:147], v[16:19]
	ds_read_b128 v[132:135], v166 offset:40960
	ds_read_b128 v[136:139], v166 offset:41472
	ds_read_b128 v[140:143], v166 offset:41984
	ds_read_b128 v[144:147], v166 offset:42496
	s_waitcnt lgkmcnt(4)
	s_waitcnt vmcnt(21)
	v_mfma_f32_16x16x32_bf16 v[12:15], v[190:193], v[148:151], v[12:15]
	v_mfma_f32_16x16x32_bf16 v[8:11], v[190:193], v[152:155], v[8:11]
	v_mfma_f32_16x16x32_bf16 v[4:7], v[190:193], v[156:159], v[4:7]
	v_mfma_f32_16x16x32_bf16 v[0:3], v[190:193], v[160:163], v[0:3]
	s_waitcnt vmcnt(20)
	v_mfma_f32_16x16x32_bf16 v[28:31], v[194:197], v[148:151], v[28:31]
	v_mfma_f32_16x16x32_bf16 v[24:27], v[194:197], v[152:155], v[24:27]
	v_mfma_f32_16x16x32_bf16 v[20:23], v[194:197], v[156:159], v[20:23]
	v_mfma_f32_16x16x32_bf16 v[16:19], v[194:197], v[160:163], v[16:19]
	ds_read_b128 v[148:151], v166 offset:45056
	ds_read_b128 v[152:155], v166 offset:45568
	ds_read_b128 v[156:159], v166 offset:46080
	ds_read_b128 v[160:163], v166 offset:46592
	s_waitcnt lgkmcnt(4)
	s_waitcnt vmcnt(19)
	v_mfma_f32_16x16x32_bf16 v[12:15], v[198:201], v[132:135], v[12:15]
	v_mfma_f32_16x16x32_bf16 v[8:11], v[198:201], v[136:139], v[8:11]
	v_mfma_f32_16x16x32_bf16 v[4:7], v[198:201], v[140:143], v[4:7]
	v_mfma_f32_16x16x32_bf16 v[0:3], v[198:201], v[144:147], v[0:3]
	s_waitcnt vmcnt(18)
	v_mfma_f32_16x16x32_bf16 v[28:31], v[202:205], v[132:135], v[28:31]
	v_mfma_f32_16x16x32_bf16 v[24:27], v[202:205], v[136:139], v[24:27]
	v_mfma_f32_16x16x32_bf16 v[20:23], v[202:205], v[140:143], v[20:23]
	v_mfma_f32_16x16x32_bf16 v[16:19], v[202:205], v[144:147], v[16:19]
	ds_read_b128 v[132:135], v166 offset:49152
	ds_read_b128 v[136:139], v166 offset:49664
	ds_read_b128 v[140:143], v166 offset:50176
	ds_read_b128 v[144:147], v166 offset:50688
	s_waitcnt lgkmcnt(4)
	s_waitcnt vmcnt(17)
	v_mfma_f32_16x16x32_bf16 v[12:15], v[206:209], v[148:151], v[12:15]
	v_mfma_f32_16x16x32_bf16 v[8:11], v[206:209], v[152:155], v[8:11]
	v_mfma_f32_16x16x32_bf16 v[4:7], v[206:209], v[156:159], v[4:7]
	v_mfma_f32_16x16x32_bf16 v[0:3], v[206:209], v[160:163], v[0:3]
	s_waitcnt vmcnt(16)
	v_mfma_f32_16x16x32_bf16 v[28:31], v[210:213], v[148:151], v[28:31]
	v_mfma_f32_16x16x32_bf16 v[24:27], v[210:213], v[152:155], v[24:27]
	v_mfma_f32_16x16x32_bf16 v[20:23], v[210:213], v[156:159], v[20:23]
	v_mfma_f32_16x16x32_bf16 v[16:19], v[210:213], v[160:163], v[16:19]
	ds_read_b128 v[148:151], v166 offset:53248
	ds_read_b128 v[152:155], v166 offset:53760
	ds_read_b128 v[156:159], v166 offset:54272
	ds_read_b128 v[160:163], v166 offset:54784
	s_waitcnt lgkmcnt(4)
	s_waitcnt vmcnt(7)
	v_mfma_f32_16x16x32_bf16 v[12:15], v[80:83], v[132:135], v[12:15]
	v_mfma_f32_16x16x32_bf16 v[8:11], v[80:83], v[136:139], v[8:11]
	v_mfma_f32_16x16x32_bf16 v[4:7], v[80:83], v[140:143], v[4:7]
	v_mfma_f32_16x16x32_bf16 v[0:3], v[80:83], v[144:147], v[0:3]
	s_waitcnt vmcnt(6)
	v_mfma_f32_16x16x32_bf16 v[28:31], v[84:87], v[132:135], v[28:31]
	v_mfma_f32_16x16x32_bf16 v[24:27], v[84:87], v[136:139], v[24:27]
	v_mfma_f32_16x16x32_bf16 v[20:23], v[84:87], v[140:143], v[20:23]
	v_mfma_f32_16x16x32_bf16 v[16:19], v[84:87], v[144:147], v[16:19]
	ds_read_b128 v[132:135], v166 offset:57344
	ds_read_b128 v[136:139], v166 offset:57856
	ds_read_b128 v[140:143], v166 offset:58368
	ds_read_b128 v[144:147], v166 offset:58880
	s_waitcnt lgkmcnt(4)
	s_waitcnt vmcnt(5)
	v_mfma_f32_16x16x32_bf16 v[12:15], v[88:91], v[148:151], v[12:15]
	v_mfma_f32_16x16x32_bf16 v[8:11], v[88:91], v[152:155], v[8:11]
	v_mfma_f32_16x16x32_bf16 v[4:7], v[88:91], v[156:159], v[4:7]
	v_mfma_f32_16x16x32_bf16 v[0:3], v[88:91], v[160:163], v[0:3]
	s_waitcnt vmcnt(4)
; #define LAS __attribute__((address_space(3)))
; __device__ __forceinline__ void ssm_stage_u(unsigned char* ws, LAS unsigned char* lds, int g, int cb, int hh, int tid) {
;     asm volatile("" : "+v"(tid));
;     const bf16* U = (const bf16*)(ws + AR_U);
;     u32x4 v[8];
; #pragma unroll
;     for (int r = 0; r < 8; ++r) { const int c = r * 512 + tid, jj = c >> 7, col = (c >> 1) & 63, part = c & 1;
;         v[r] = *(const u32x4*)(U + ((size_t)((cb * 64 + col) * 64 + hh * 32 + jj) * 512 + g * 16 + part * 8)); }
; #pragma unroll
;     for (int r = 0; r < 8; ++r) { const int c = r * 512 + tid; *(LAS u32x4*)(lds + SS_UB + c * 16) = v[r]; }
; }
; __device__ __forceinline__ void ssm_a_task(unsigned char* ws, LAS unsigned char* lds, int task, int tid) {
;     ...
;         for (int ks = 0; ks < 16; ++ks) {
;             bf16x8 bfr[4], afr[2];
; #pragma unroll
;             for (int a = 0; a < 2; ++a) afr[a] = *(const bf16x8*)(WA + (size_t)a * 16 * 1024 + (hh * 16 + ks) * 32);
; #pragma unroll
;             for (int c = 0; c < 4; ++c) bfr[c] = *(const LAS bf16x8*)(lds + SS_UB + (((2 * ks + (kk >> 1)) * 64 + c * 16 + rr) * 32 + (kk & 1) * 16));
; #pragma unroll
;             for (int a = 0; a < 2; ++a)
; #pragma unroll
;                 for (int c = 0; c < 4; ++c) acc[a][c] = __builtin_amdgcn_mfma_f32_16x16x32_bf16(afr[a], bfr[c], acc[a][c], 0, 0, 0);
;         }
;         __syncthreads();
	v_mfma_f32_16x16x32_bf16 v[28:31], v[92:95], v[148:151], v[28:31]
	v_mfma_f32_16x16x32_bf16 v[24:27], v[92:95], v[152:155], v[24:27]
	v_mfma_f32_16x16x32_bf16 v[20:23], v[92:95], v[156:159], v[20:23]
	v_mfma_f32_16x16x32_bf16 v[16:19], v[92:95], v[160:163], v[16:19]
	ds_read_b128 v[148:151], v166 offset:61440
	ds_read_b128 v[152:155], v166 offset:61952
	ds_read_b128 v[156:159], v166 offset:62464
	ds_read_b128 v[160:163], v166 offset:62976
	s_waitcnt lgkmcnt(4)
	s_waitcnt vmcnt(3)
	v_mfma_f32_16x16x32_bf16 v[12:15], v[96:99], v[132:135], v[12:15]
	v_mfma_f32_16x16x32_bf16 v[8:11], v[96:99], v[136:139], v[8:11]
	v_mfma_f32_16x16x32_bf16 v[4:7], v[96:99], v[140:143], v[4:7]
	v_mfma_f32_16x16x32_bf16 v[0:3], v[96:99], v[144:147], v[0:3]
	s_waitcnt vmcnt(2)
	v_mfma_f32_16x16x32_bf16 v[28:31], v[100:103], v[132:135], v[28:31]
	v_mfma_f32_16x16x32_bf16 v[24:27], v[100:103], v[136:139], v[24:27]
	v_mfma_f32_16x16x32_bf16 v[20:23], v[100:103], v[140:143], v[20:23]
	v_mfma_f32_16x16x32_bf16 v[16:19], v[100:103], v[144:147], v[16:19]
	s_waitcnt lgkmcnt(0)
	s_waitcnt vmcnt(1)
	v_mfma_f32_16x16x32_bf16 v[12:15], v[104:107], v[148:151], v[12:15]
	v_mfma_f32_16x16x32_bf16 v[8:11], v[104:107], v[152:155], v[8:11]
	v_mfma_f32_16x16x32_bf16 v[4:7], v[104:107], v[156:159], v[4:7]
	v_mfma_f32_16x16x32_bf16 v[0:3], v[104:107], v[160:163], v[0:3]
	s_waitcnt vmcnt(0)
	v_mfma_f32_16x16x32_bf16 v[28:31], v[108:111], v[148:151], v[28:31]
	v_mfma_f32_16x16x32_bf16 v[24:27], v[108:111], v[152:155], v[24:27]
	v_mfma_f32_16x16x32_bf16 v[20:23], v[108:111], v[156:159], v[20:23]
	v_mfma_f32_16x16x32_bf16 v[16:19], v[108:111], v[160:163], v[16:19]
	s_mov_b32 s12, 0x10000
	v_mov_b32_e32 v72, v44
	s_barrier
	v_lshl_add_u64 v[38:39], v[36:37], 0, v[38:39]
	v_lshlrev_b32_e32 v40, 5, v72
	v_and_b32_e32 v40, 0xfc0, v40
	v_or3_b32 v73, s3, v40, 32
	v_lshlrev_b32_e32 v76, 4, v72
	v_ashrrev_i32_e32 v40, 7, v72
	v_add_u32_e32 v42, 0x200, v72
	v_add_u32_e32 v52, 0x400, v72
	v_add_u32_e32 v54, 0x600, v72
	v_add_u32_e32 v60, 0x800, v72
	v_add_u32_e32 v62, 0xa00, v72
	v_add_u32_e32 v70, 0xc00, v72
	v_add_u32_e32 v72, 0xe00, v72
	v_ashrrev_i32_e32 v42, 7, v42
	v_ashrrev_i32_e32 v52, 7, v52
	v_ashrrev_i32_e32 v54, 7, v54
	v_ashrrev_i32_e32 v60, 7, v60
	v_ashrrev_i32_e32 v62, 7, v62
	v_ashrrev_i32_e32 v70, 7, v70
	v_ashrrev_i32_e32 v72, 7, v72
	v_add_u32_e32 v40, v73, v40
	v_add_u32_e32 v42, v73, v42
	v_add_u32_e32 v52, v73, v52
	v_add_u32_e32 v54, v73, v54
	v_add_u32_e32 v60, v73, v60
	v_add_u32_e32 v62, v73, v62
	v_add_u32_e32 v70, v73, v70
	v_add_u32_e32 v72, v73, v72
	v_and_b32_e32 v184, 16, v76
	v_ashrrev_i32_e32 v41, 31, v40
	v_ashrrev_i32_e32 v43, 31, v42
	v_ashrrev_i32_e32 v53, 31, v52
	v_ashrrev_i32_e32 v55, 31, v54
	v_ashrrev_i32_e32 v61, 31, v60
	v_ashrrev_i32_e32 v63, 31, v62
	v_ashrrev_i32_e32 v71, 31, v70
	v_ashrrev_i32_e32 v73, 31, v72
	v_lshl_add_u64 v[68:69], s[34:35], 0, v[184:185]
	v_lshlrev_b64 v[40:41], 10, v[40:41]
	v_lshlrev_b64 v[42:43], 10, v[42:43]
	v_lshlrev_b64 v[52:53], 10, v[52:53]
	v_lshlrev_b64 v[54:55], 10, v[54:55]
	v_lshlrev_b64 v[60:61], 10, v[60:61]
	v_lshlrev_b64 v[62:63], 10, v[62:63]
	v_lshlrev_b64 v[70:71], 10, v[70:71]
	v_lshlrev_b64 v[72:73], 10, v[72:73]
	v_lshl_add_u64 v[40:41], v[68:69], 0, v[40:41]
	v_lshl_add_u64 v[48:49], v[68:69], 0, v[42:43]
	v_lshl_add_u64 v[52:53], v[68:69], 0, v[52:53]
	v_lshl_add_u64 v[56:57], v[68:69], 0, v[54:55]
	v_lshl_add_u64 v[60:61], v[68:69], 0, v[60:61]
	v_lshl_add_u64 v[64:65], v[68:69], 0, v[62:63]
	v_lshl_add_u64 v[70:71], v[68:69], 0, v[70:71]
	v_lshl_add_u64 v[72:73], v[68:69], 0, v[72:73]
	s_nop 0
	s_nop 0
	s_nop 0
	s_nop 0
	s_nop 0
	s_nop 0
	s_nop 0
	v_add_u32_e32 v76, 0, v76
	v_add_u32_e32 v76, 0x10000, v76
	s_mov_b32 s3, 0
	v_add_co_u32_e32 v164, vcc, 0xffff8000, v38
	s_nop 1
	v_addc_co_u32_e32 v165, vcc, -1, v39, vcc
	global_load_dwordx4 v[80:83], v[38:39], off offset:-192
	global_load_dwordx4 v[84:87], v[164:165], off offset:-192
	global_load_dwordx4 v[88:91], v[38:39], off offset:-128
	global_load_dwordx4 v[92:95], v[164:165], off offset:-128
	global_load_dwordx4 v[96:99], v[38:39], off offset:-64
	global_load_dwordx4 v[100:103], v[164:165], off offset:-64
	global_load_dwordx4 v[104:107], v[38:39], off offset:0
	global_load_dwordx4 v[108:111], v[164:165], off offset:0
	global_load_dwordx4 v[112:115], v[38:39], off offset:64
	global_load_dwordx4 v[116:119], v[164:165], off offset:64
	global_load_dwordx4 v[120:123], v[38:39], off offset:128
	global_load_dwordx4 v[124:127], v[164:165], off offset:128
	global_load_dwordx4 v[128:131], v[38:39], off offset:192
	global_load_dwordx4 v[168:171], v[164:165], off offset:192
	global_load_dwordx4 v[172:175], v[38:39], off offset:256
	global_load_dwordx4 v[176:179], v[164:165], off offset:256
	global_load_dwordx4 v[180:183], v[38:39], off offset:320
	global_load_dwordx4 v[186:189], v[164:165], off offset:320
	global_load_dwordx4 v[190:193], v[38:39], off offset:384
	global_load_dwordx4 v[194:197], v[164:165], off offset:384
	global_load_dwordx4 v[198:201], v[38:39], off offset:448
	global_load_dwordx4 v[202:205], v[164:165], off offset:448
	global_load_dwordx4 v[206:209], v[38:39], off offset:512
	global_load_dwordx4 v[210:213], v[164:165], off offset:512
	s_waitcnt vmcnt(24)
	s_waitcnt lgkmcnt(0)
	s_barrier
; #define LAS __attribute__((address_space(3)))
; __device__ __forceinline__ void ssm_a_task(unsigned char* ws, LAS unsigned char* lds, int task, int tid) {
;     ...
; #pragma unroll 4
;         for (int ks = 0; ks < 16; ++ks) {
;             bf16x8 bfr[4], afr[2];
; #pragma unroll
;             for (int a = 0; a < 2; ++a) afr[a] = *(const bf16x8*)(WA + (size_t)a * 16 * 1024 + (hh * 16 + ks) * 32);
; #pragma unroll
;             for (int c = 0; c < 4; ++c) bfr[c] = *(const LAS bf16x8*)(lds + SS_UB + (((2 * ks + (kk >> 1)) * 64 + c * 16 + rr) * 32 + (kk & 1) * 16));
; #pragma unroll
;             for (int a = 0; a < 2; ++a)
; #pragma unroll
;                 for (int c = 0; c < 4; ++c) acc[a][c] = __builtin_amdgcn_mfma_f32_16x16x32_bf16(afr[a], bfr[c], acc[a][c], 0, 0, 0);
;         }
.LBB0_606:
	v_mov_b32_e32 v166, v47
	ds_read_b128 v[132:135], v166 offset:0
	ds_read_b128 v[136:139], v166 offset:512
	ds_read_b128 v[140:143], v166 offset:1024
	ds_read_b128 v[144:147], v166 offset:1536
	ds_read_b128 v[148:151], v166 offset:4096
	ds_read_b128 v[152:155], v166 offset:4608
	ds_read_b128 v[156:159], v166 offset:5120
	ds_read_b128 v[160:163], v166 offset:5632
	s_waitcnt lgkmcnt(4)
	s_waitcnt vmcnt(23)
	v_mfma_f32_16x16x32_bf16 v[12:15], v[80:83], v[132:135], v[12:15]
	v_mfma_f32_16x16x32_bf16 v[8:11], v[80:83], v[136:139], v[8:11]
	v_mfma_f32_16x16x32_bf16 v[4:7], v[80:83], v[140:143], v[4:7]
	v_mfma_f32_16x16x32_bf16 v[0:3], v[80:83], v[144:147], v[0:3]
	s_waitcnt vmcnt(22)
	v_mfma_f32_16x16x32_bf16 v[28:31], v[84:87], v[132:135], v[28:31]
	v_mfma_f32_16x16x32_bf16 v[24:27], v[84:87], v[136:139], v[24:27]
	v_mfma_f32_16x16x32_bf16 v[20:23], v[84:87], v[140:143], v[20:23]
	v_mfma_f32_16x16x32_bf16 v[16:19], v[84:87], v[144:147], v[16:19]
	global_load_dwordx4 v[80:83], v[38:39], off offset:576
	global_load_dwordx4 v[84:87], v[164:165], off offset:576
	ds_read_b128 v[132:135], v166 offset:8192
	ds_read_b128 v[136:139], v166 offset:8704
	ds_read_b128 v[140:143], v166 offset:9216
	ds_read_b128 v[144:147], v166 offset:9728
	s_waitcnt lgkmcnt(4)
	s_waitcnt vmcnt(23)
	v_mfma_f32_16x16x32_bf16 v[12:15], v[88:91], v[148:151], v[12:15]
	v_mfma_f32_16x16x32_bf16 v[8:11], v[88:91], v[152:155], v[8:11]
	v_mfma_f32_16x16x32_bf16 v[4:7], v[88:91], v[156:159], v[4:7]
	v_mfma_f32_16x16x32_bf16 v[0:3], v[88:91], v[160:163], v[0:3]
	s_waitcnt vmcnt(22)
	v_mfma_f32_16x16x32_bf16 v[28:31], v[92:95], v[148:151], v[28:31]
	v_mfma_f32_16x16x32_bf16 v[24:27], v[92:95], v[152:155], v[24:27]
	v_mfma_f32_16x16x32_bf16 v[20:23], v[92:95], v[156:159], v[20:23]
	v_mfma_f32_16x16x32_bf16 v[16:19], v[92:95], v[160:163], v[16:19]
	global_load_dwordx4 v[88:91], v[38:39], off offset:640
	global_load_dwordx4 v[92:95], v[164:165], off offset:640
	ds_read_b128 v[148:151], v166 offset:12288
	ds_read_b128 v[152:155], v166 offset:12800
	ds_read_b128 v[156:159], v166 offset:13312
	ds_read_b128 v[160:163], v166 offset:13824
	s_waitcnt lgkmcnt(4)
	s_waitcnt vmcnt(23)
	v_mfma_f32_16x16x32_bf16 v[12:15], v[96:99], v[132:135], v[12:15]
	v_mfma_f32_16x16x32_bf16 v[8:11], v[96:99], v[136:139], v[8:11]
	v_mfma_f32_16x16x32_bf16 v[4:7], v[96:99], v[140:143], v[4:7]
	v_mfma_f32_16x16x32_bf16 v[0:3], v[96:99], v[144:147], v[0:3]
	s_waitcnt vmcnt(22)
	v_mfma_f32_16x16x32_bf16 v[28:31], v[100:103], v[132:135], v[28:31]
	v_mfma_f32_16x16x32_bf16 v[24:27], v[100:103], v[136:139], v[24:27]
	v_mfma_f32_16x16x32_bf16 v[20:23], v[100:103], v[140:143], v[20:23]
	v_mfma_f32_16x16x32_bf16 v[16:19], v[100:103], v[144:147], v[16:19]
	global_load_dwordx4 v[96:99], v[38:39], off offset:704
	global_load_dwordx4 v[100:103], v[164:165], off offset:704
	ds_read_b128 v[132:135], v166 offset:16384
	ds_read_b128 v[136:139], v166 offset:16896
	ds_read_b128 v[140:143], v166 offset:17408
	ds_read_b128 v[144:147], v166 offset:17920
	s_waitcnt lgkmcnt(4)
	s_waitcnt vmcnt(23)
	v_mfma_f32_16x16x32_bf16 v[12:15], v[104:107], v[148:151], v[12:15]
	v_mfma_f32_16x16x32_bf16 v[8:11], v[104:107], v[152:155], v[8:11]
	v_mfma_f32_16x16x32_bf16 v[4:7], v[104:107], v[156:159], v[4:7]
	v_mfma_f32_16x16x32_bf16 v[0:3], v[104:107], v[160:163], v[0:3]
	s_waitcnt vmcnt(22)
	v_mfma_f32_16x16x32_bf16 v[28:31], v[108:111], v[148:151], v[28:31]
	v_mfma_f32_16x16x32_bf16 v[24:27], v[108:111], v[152:155], v[24:27]
	v_mfma_f32_16x16x32_bf16 v[20:23], v[108:111], v[156:159], v[20:23]
	v_mfma_f32_16x16x32_bf16 v[16:19], v[108:111], v[160:163], v[16:19]
	global_load_dwordx4 v[104:107], v[38:39], off offset:768
	global_load_dwordx4 v[108:111], v[164:165], off offset:768
	ds_read_b128 v[148:151], v166 offset:20480
	ds_read_b128 v[152:155], v166 offset:20992
	ds_read_b128 v[156:159], v166 offset:21504
	ds_read_b128 v[160:163], v166 offset:22016
	s_waitcnt lgkmcnt(4)
	s_waitcnt vmcnt(23)
	v_mfma_f32_16x16x32_bf16 v[12:15], v[112:115], v[132:135], v[12:15]
	v_mfma_f32_16x16x32_bf16 v[8:11], v[112:115], v[136:139], v[8:11]
	v_mfma_f32_16x16x32_bf16 v[4:7], v[112:115], v[140:143], v[4:7]
	v_mfma_f32_16x16x32_bf16 v[0:3], v[112:115], v[144:147], v[0:3]
	s_waitcnt vmcnt(22)
	v_mfma_f32_16x16x32_bf16 v[28:31], v[116:119], v[132:135], v[28:31]
	v_mfma_f32_16x16x32_bf16 v[24:27], v[116:119], v[136:139], v[24:27]
	v_mfma_f32_16x16x32_bf16 v[20:23], v[116:119], v[140:143], v[20:23]
	v_mfma_f32_16x16x32_bf16 v[16:19], v[116:119], v[144:147], v[16:19]
	ds_read_b128 v[132:135], v166 offset:24576
	ds_read_b128 v[136:139], v166 offset:25088
	ds_read_b128 v[140:143], v166 offset:25600
	ds_read_b128 v[144:147], v166 offset:26112
	s_waitcnt lgkmcnt(4)
	s_waitcnt vmcnt(21)
	v_mfma_f32_16x16x32_bf16 v[12:15], v[120:123], v[148:151], v[12:15]
	v_mfma_f32_16x16x32_bf16 v[8:11], v[120:123], v[152:155], v[8:11]
	v_mfma_f32_16x16x32_bf16 v[4:7], v[120:123], v[156:159], v[4:7]
	v_mfma_f32_16x16x32_bf16 v[0:3], v[120:123], v[160:163], v[0:3]
	s_waitcnt vmcnt(20)
	v_mfma_f32_16x16x32_bf16 v[28:31], v[124:127], v[148:151], v[28:31]
	v_mfma_f32_16x16x32_bf16 v[24:27], v[124:127], v[152:155], v[24:27]
	v_mfma_f32_16x16x32_bf16 v[20:23], v[124:127], v[156:159], v[20:23]
	v_mfma_f32_16x16x32_bf16 v[16:19], v[124:127], v[160:163], v[16:19]
	ds_read_b128 v[148:151], v166 offset:28672
	ds_read_b128 v[152:155], v166 offset:29184
	ds_read_b128 v[156:159], v166 offset:29696
	ds_read_b128 v[160:163], v166 offset:30208
	s_waitcnt lgkmcnt(4)
	s_waitcnt vmcnt(19)
; #define LAS __attribute__((address_space(3)))
; __device__ __forceinline__ void ssm_a_task(unsigned char* ws, LAS unsigned char* lds, int task, int tid) {
;     ...
; #pragma unroll 4
;         for (int ks = 0; ks < 16; ++ks) {
;             bf16x8 bfr[4], afr[2];
; #pragma unroll
;             for (int a = 0; a < 2; ++a) afr[a] = *(const bf16x8*)(WA + (size_t)a * 16 * 1024 + (hh * 16 + ks) * 32);
; #pragma unroll
;             for (int c = 0; c < 4; ++c) bfr[c] = *(const LAS bf16x8*)(lds + SS_UB + (((2 * ks + (kk >> 1)) * 64 + c * 16 + rr) * 32 + (kk & 1) * 16));
; #pragma unroll
;             for (int a = 0; a < 2; ++a)
; #pragma unroll
;                 for (int c = 0; c < 4; ++c) acc[a][c] = __builtin_amdgcn_mfma_f32_16x16x32_bf16(afr[a], bfr[c], acc[a][c], 0, 0, 0);
;         }
	v_mfma_f32_16x16x32_bf16 v[12:15], v[128:131], v[132:135], v[12:15]
	v_mfma_f32_16x16x32_bf16 v[8:11], v[128:131], v[136:139], v[8:11]
	v_mfma_f32_16x16x32_bf16 v[4:7], v[128:131], v[140:143], v[4:7]
	v_mfma_f32_16x16x32_bf16 v[0:3], v[128:131], v[144:147], v[0:3]
	s_waitcnt vmcnt(18)
	v_mfma_f32_16x16x32_bf16 v[28:31], v[168:171], v[132:135], v[28:31]
	v_mfma_f32_16x16x32_bf16 v[24:27], v[168:171], v[136:139], v[24:27]
	v_mfma_f32_16x16x32_bf16 v[20:23], v[168:171], v[140:143], v[20:23]
	v_mfma_f32_16x16x32_bf16 v[16:19], v[168:171], v[144:147], v[16:19]
	ds_read_b128 v[132:135], v166 offset:32768
	ds_read_b128 v[136:139], v166 offset:33280
	ds_read_b128 v[140:143], v166 offset:33792
	ds_read_b128 v[144:147], v166 offset:34304
	s_waitcnt lgkmcnt(4)
	s_waitcnt vmcnt(17)
	v_mfma_f32_16x16x32_bf16 v[12:15], v[172:175], v[148:151], v[12:15]
	v_mfma_f32_16x16x32_bf16 v[8:11], v[172:175], v[152:155], v[8:11]
	v_mfma_f32_16x16x32_bf16 v[4:7], v[172:175], v[156:159], v[4:7]
	v_mfma_f32_16x16x32_bf16 v[0:3], v[172:175], v[160:163], v[0:3]
	s_waitcnt vmcnt(16)
	v_mfma_f32_16x16x32_bf16 v[28:31], v[176:179], v[148:151], v[28:31]
	v_mfma_f32_16x16x32_bf16 v[24:27], v[176:179], v[152:155], v[24:27]
	v_mfma_f32_16x16x32_bf16 v[20:23], v[176:179], v[156:159], v[20:23]
	v_mfma_f32_16x16x32_bf16 v[16:19], v[176:179], v[160:163], v[16:19]
	ds_read_b128 v[148:151], v166 offset:36864
	ds_read_b128 v[152:155], v166 offset:37376
	ds_read_b128 v[156:159], v166 offset:37888
	ds_read_b128 v[160:163], v166 offset:38400
	s_waitcnt lgkmcnt(4)
	s_waitcnt vmcnt(15)
	v_mfma_f32_16x16x32_bf16 v[12:15], v[180:183], v[132:135], v[12:15]
	v_mfma_f32_16x16x32_bf16 v[8:11], v[180:183], v[136:139], v[8:11]
	v_mfma_f32_16x16x32_bf16 v[4:7], v[180:183], v[140:143], v[4:7]
	v_mfma_f32_16x16x32_bf16 v[0:3], v[180:183], v[144:147], v[0:3]
	s_waitcnt vmcnt(14)
	v_mfma_f32_16x16x32_bf16 v[28:31], v[186:189], v[132:135], v[28:31]
	v_mfma_f32_16x16x32_bf16 v[24:27], v[186:189], v[136:139], v[24:27]
	v_mfma_f32_16x16x32_bf16 v[20:23], v[186:189], v[140:143], v[20:23]
	v_mfma_f32_16x16x32_bf16 v[16:19], v[186:189], v[144:147], v[16:19]
	ds_read_b128 v[132:135], v166 offset:40960
	ds_read_b128 v[136:139], v166 offset:41472
	ds_read_b128 v[140:143], v166 offset:41984
	ds_read_b128 v[144:147], v166 offset:42496
	s_waitcnt lgkmcnt(4)
	s_waitcnt vmcnt(13)
	v_mfma_f32_16x16x32_bf16 v[12:15], v[190:193], v[148:151], v[12:15]
	v_mfma_f32_16x16x32_bf16 v[8:11], v[190:193], v[152:155], v[8:11]
	v_mfma_f32_16x16x32_bf16 v[4:7], v[190:193], v[156:159], v[4:7]
	v_mfma_f32_16x16x32_bf16 v[0:3], v[190:193], v[160:163], v[0:3]
	s_waitcnt vmcnt(12)
	v_mfma_f32_16x16x32_bf16 v[28:31], v[194:197], v[148:151], v[28:31]
	v_mfma_f32_16x16x32_bf16 v[24:27], v[194:197], v[152:155], v[24:27]
	v_mfma_f32_16x16x32_bf16 v[20:23], v[194:197], v[156:159], v[20:23]
	v_mfma_f32_16x16x32_bf16 v[16:19], v[194:197], v[160:163], v[16:19]
	ds_read_b128 v[148:151], v166 offset:45056
	ds_read_b128 v[152:155], v166 offset:45568
	ds_read_b128 v[156:159], v166 offset:46080
	ds_read_b128 v[160:163], v166 offset:46592
	s_waitcnt lgkmcnt(4)
	s_waitcnt vmcnt(11)
	v_mfma_f32_16x16x32_bf16 v[12:15], v[198:201], v[132:135], v[12:15]
	v_mfma_f32_16x16x32_bf16 v[8:11], v[198:201], v[136:139], v[8:11]
	v_mfma_f32_16x16x32_bf16 v[4:7], v[198:201], v[140:143], v[4:7]
	v_mfma_f32_16x16x32_bf16 v[0:3], v[198:201], v[144:147], v[0:3]
	s_waitcnt vmcnt(10)
	v_mfma_f32_16x16x32_bf16 v[28:31], v[202:205], v[132:135], v[28:31]
	v_mfma_f32_16x16x32_bf16 v[24:27], v[202:205], v[136:139], v[24:27]
	v_mfma_f32_16x16x32_bf16 v[20:23], v[202:205], v[140:143], v[20:23]
	v_mfma_f32_16x16x32_bf16 v[16:19], v[202:205], v[144:147], v[16:19]
	ds_read_b128 v[132:135], v166 offset:49152
	ds_read_b128 v[136:139], v166 offset:49664
	ds_read_b128 v[140:143], v166 offset:50176
	ds_read_b128 v[144:147], v166 offset:50688
	s_waitcnt lgkmcnt(4)
	s_waitcnt vmcnt(9)
	v_mfma_f32_16x16x32_bf16 v[12:15], v[206:209], v[148:151], v[12:15]
	v_mfma_f32_16x16x32_bf16 v[8:11], v[206:209], v[152:155], v[8:11]
	v_mfma_f32_16x16x32_bf16 v[4:7], v[206:209], v[156:159], v[4:7]
	v_mfma_f32_16x16x32_bf16 v[0:3], v[206:209], v[160:163], v[0:3]
	s_waitcnt vmcnt(8)
; #define LAS __attribute__((address_space(3)))
; __device__ __forceinline__ void ssm_a_task(unsigned char* ws, LAS unsigned char* lds, int task, int tid) {
;     ...
;         for (int ks = 0; ks < 16; ++ks) {
;             bf16x8 bfr[4], afr[2];
; #pragma unroll
;             for (int a = 0; a < 2; ++a) afr[a] = *(const bf16x8*)(WA + (size_t)a * 16 * 1024 + (hh * 16 + ks) * 32);
; #pragma unroll
;             for (int c = 0; c < 4; ++c) bfr[c] = *(const LAS bf16x8*)(lds + SS_UB + (((2 * ks + (kk >> 1)) * 64 + c * 16 + rr) * 32 + (kk & 1) * 16));
; #pragma unroll
;             for (int a = 0; a < 2; ++a)
; #pragma unroll
;                 for (int c = 0; c < 4; ++c) acc[a][c] = __builtin_amdgcn_mfma_f32_16x16x32_bf16(afr[a], bfr[c], acc[a][c], 0, 0, 0);
;         }
;         __syncthreads();
;     }
;     float* S = (float*)(ws + AR_S);
; #pragma unroll
;     for (int a = 0; a < 2; ++a)
; #pragma unroll
;         for (int c = 0; c < 4; ++c) { const int col = cb * 64 + c * 16 + rr; *(f32x4*)(S + ((size_t)(col * NG + g) * 256 + wid * 32 + a * 16 + 4 * kk)) = acc[a][c]; }
	v_mfma_f32_16x16x32_bf16 v[28:31], v[210:213], v[148:151], v[28:31]
	v_mfma_f32_16x16x32_bf16 v[24:27], v[210:213], v[152:155], v[24:27]
	v_mfma_f32_16x16x32_bf16 v[20:23], v[210:213], v[156:159], v[20:23]
	v_mfma_f32_16x16x32_bf16 v[16:19], v[210:213], v[160:163], v[16:19]
	ds_read_b128 v[148:151], v166 offset:53248
	ds_read_b128 v[152:155], v166 offset:53760
	ds_read_b128 v[156:159], v166 offset:54272
	ds_read_b128 v[160:163], v166 offset:54784
	s_waitcnt lgkmcnt(4)
	s_waitcnt vmcnt(7)
	v_mfma_f32_16x16x32_bf16 v[12:15], v[80:83], v[132:135], v[12:15]
	v_mfma_f32_16x16x32_bf16 v[8:11], v[80:83], v[136:139], v[8:11]
	v_mfma_f32_16x16x32_bf16 v[4:7], v[80:83], v[140:143], v[4:7]
	v_mfma_f32_16x16x32_bf16 v[0:3], v[80:83], v[144:147], v[0:3]
	s_waitcnt vmcnt(6)
	v_mfma_f32_16x16x32_bf16 v[28:31], v[84:87], v[132:135], v[28:31]
	v_mfma_f32_16x16x32_bf16 v[24:27], v[84:87], v[136:139], v[24:27]
	v_mfma_f32_16x16x32_bf16 v[20:23], v[84:87], v[140:143], v[20:23]
	v_mfma_f32_16x16x32_bf16 v[16:19], v[84:87], v[144:147], v[16:19]
	ds_read_b128 v[132:135], v166 offset:57344
	ds_read_b128 v[136:139], v166 offset:57856
	ds_read_b128 v[140:143], v166 offset:58368
	ds_read_b128 v[144:147], v166 offset:58880
	s_waitcnt lgkmcnt(4)
	s_waitcnt vmcnt(5)
	v_mfma_f32_16x16x32_bf16 v[12:15], v[88:91], v[148:151], v[12:15]
	v_mfma_f32_16x16x32_bf16 v[8:11], v[88:91], v[152:155], v[8:11]
	v_mfma_f32_16x16x32_bf16 v[4:7], v[88:91], v[156:159], v[4:7]
	v_mfma_f32_16x16x32_bf16 v[0:3], v[88:91], v[160:163], v[0:3]
	s_waitcnt vmcnt(4)
	v_mfma_f32_16x16x32_bf16 v[28:31], v[92:95], v[148:151], v[28:31]
	v_mfma_f32_16x16x32_bf16 v[24:27], v[92:95], v[152:155], v[24:27]
	v_mfma_f32_16x16x32_bf16 v[20:23], v[92:95], v[156:159], v[20:23]
	v_mfma_f32_16x16x32_bf16 v[16:19], v[92:95], v[160:163], v[16:19]
	ds_read_b128 v[148:151], v166 offset:61440
	ds_read_b128 v[152:155], v166 offset:61952
	ds_read_b128 v[156:159], v166 offset:62464
	ds_read_b128 v[160:163], v166 offset:62976
	s_waitcnt lgkmcnt(4)
	s_waitcnt vmcnt(3)
	v_mfma_f32_16x16x32_bf16 v[12:15], v[96:99], v[132:135], v[12:15]
	v_mfma_f32_16x16x32_bf16 v[8:11], v[96:99], v[136:139], v[8:11]
	v_mfma_f32_16x16x32_bf16 v[4:7], v[96:99], v[140:143], v[4:7]
	v_mfma_f32_16x16x32_bf16 v[0:3], v[96:99], v[144:147], v[0:3]
	s_waitcnt vmcnt(2)
	v_mfma_f32_16x16x32_bf16 v[28:31], v[100:103], v[132:135], v[28:31]
	v_mfma_f32_16x16x32_bf16 v[24:27], v[100:103], v[136:139], v[24:27]
	v_mfma_f32_16x16x32_bf16 v[20:23], v[100:103], v[140:143], v[20:23]
	v_mfma_f32_16x16x32_bf16 v[16:19], v[100:103], v[144:147], v[16:19]
	s_waitcnt lgkmcnt(0)
	s_waitcnt vmcnt(1)
	v_mfma_f32_16x16x32_bf16 v[12:15], v[104:107], v[148:151], v[12:15]
	v_mfma_f32_16x16x32_bf16 v[8:11], v[104:107], v[152:155], v[8:11]
	v_mfma_f32_16x16x32_bf16 v[4:7], v[104:107], v[156:159], v[4:7]
	v_mfma_f32_16x16x32_bf16 v[0:3], v[104:107], v[160:163], v[0:3]
	s_waitcnt vmcnt(0)
	v_mfma_f32_16x16x32_bf16 v[28:31], v[108:111], v[148:151], v[28:31]
	v_mfma_f32_16x16x32_bf16 v[24:27], v[108:111], v[152:155], v[24:27]
	v_mfma_f32_16x16x32_bf16 v[20:23], v[108:111], v[156:159], v[20:23]
	v_mfma_f32_16x16x32_bf16 v[16:19], v[108:111], v[160:163], v[16:19]
	s_mov_b32 s3, 0x10000
	v_lshl_or_b32 v38, s17, 11, v45
	v_add_u32_e32 v38, s16, v38
	v_ashrrev_i32_e32 v39, 31, v38
	v_lshlrev_b64 v[40:41], 10, v[38:39]
	v_lshl_add_u64 v[40:41], v[32:33], 0, v[40:41]
	s_barrier
	global_store_dwordx4 v[40:41], v[28:31], off
	s_add_i32 s54, s54, s76
	s_cmpk_gt_i32 s54, 0xff
	v_add_u32_e32 v28, 0x200, v38
	v_ashrrev_i32_e32 v29, 31, v28
	v_lshlrev_b64 v[28:29], 10, v[28:29]
	v_lshl_add_u64 v[28:29], v[32:33], 0, v[28:29]
	global_store_dwordx4 v[28:29], v[24:27], off
	s_nop 1
	v_add_u32_e32 v24, 0x400, v38
	v_ashrrev_i32_e32 v25, 31, v24
	v_lshlrev_b64 v[24:25], 10, v[24:25]
	v_lshl_add_u64 v[24:25], v[32:33], 0, v[24:25]
	global_store_dwordx4 v[24:25], v[20:23], off
	s_nop 1
	v_add_u32_e32 v20, 0x600, v38
	v_ashrrev_i32_e32 v21, 31, v20
	v_lshlrev_b64 v[20:21], 10, v[20:21]
	v_lshl_add_u64 v[20:21], v[32:33], 0, v[20:21]
	global_store_dwordx4 v[20:21], v[16:19], off
	global_store_dwordx4 v[40:41], v[12:15], off offset:64
	global_store_dwordx4 v[28:29], v[8:11], off offset:64
	global_store_dwordx4 v[24:25], v[4:7], off offset:64
	global_store_dwordx4 v[20:21], v[0:3], off offset:64
	s_cbranch_scc0 .LBB0_603
